# v79: v68 without the s_sleep between polls in the follower / leader / TOPGEN poll loops of the two group-wide seams
# speedup vs baseline: 1.0029x; 1.0005x over previous
.Lhb_fspin_g1:
	global_load_dword v6, v4, s[100:101] offset:-1024 sc1
	s_add_i32 s99, s99, 1
	s_waitcnt vmcnt(0)
	v_readfirstlane_b32 vcc_lo, v6
	s_cmp_ge_u32 vcc_lo, s98
	s_cbranch_scc1 .Lhb_done_g1
	s_cmp_lt_u32 s99, 0x2000
	s_cbranch_scc1 .Lhb_fspin_g1
	s_branch .Lhb_done_g1

.Lhb_lspin_g1:
	global_load_dword v6, v4, s[100:101] sc1
	v_add_u32_e32 v5, 1, v5
	s_waitcnt vmcnt(0)
	v_cmp_gt_u32_e32 vcc, s98, v6
	s_cmp_eq_u64 vcc, 0
	s_cbranch_scc1 .Lhb_ltop_g1
	v_readfirstlane_b32 vcc_lo, v5
	s_cmp_lt_u32 vcc_lo, 0x2000
	s_cbranch_scc1 .Lhb_lspin_g1
.Lhb_ltop_g1:
	s_mov_b64 exec, 1
	buffer_wbl2 sc1
	v_readlane_b32 vcc_lo, v255, 55
	v_readlane_b32 vcc_hi, v254, 7
	s_nop 1
	s_add_i32 vcc_lo, vcc_lo, 1
	v_mov_b32_e32 v2, vcc_hi
	v_writelane_b32 v255, vcc_lo, 55
	v_mov_b32_e32 v0, vcc_lo
	v_readlane_b32 vcc_hi, v254, 8
	v_mov_b32_e32 v5, 1
	s_nop 1
	v_mov_b32_e32 v3, vcc_hi
	s_waitcnt vmcnt(0)
	global_atomic_add v6, v[2:3], v5, off sc0
	v_readlane_b32 vcc_lo, v254, 9
	v_readlane_b32 vcc_hi, v254, 10
	v_lshlrev_b32_e32 v4, 2, v0
	s_waitcnt vmcnt(0)
	v_mov_b32_e32 v2, vcc_lo
	v_mov_b32_e32 v3, vcc_hi
	v_add_u32_e32 v6, 1, v6
	s_nop 0
	v_cmp_eq_u32_e32 vcc, v6, v4
	s_cbranch_vccz .Lhb_twait_g1
	global_atomic_add v[2:3], v5, off
	s_branch .Lhb_lrel_g1

.Lhb_tspin_g1:
	global_load_dword v6, v[2:3], off sc1
	v_add_u32_e32 v4, 1, v4
	s_waitcnt vmcnt(0)
	v_cmp_ge_u32_e32 vcc, v6, v0
	s_cbranch_vccnz .Lhb_lrel_g1
	v_cmp_gt_u32_e32 vcc, 0x40000, v4
	s_cbranch_vccnz .Lhb_tspin_g1

.Lhb_lspin_mix:
	global_load_dword v6, v4, s[100:101] sc1
	v_add_u32_e32 v5, 1, v5
	s_waitcnt vmcnt(0)
	v_cmp_gt_u32_e32 vcc, s98, v6
	s_cmp_eq_u64 vcc, 0
	s_cbranch_scc1 .Lhb_ltop_mix
	v_readfirstlane_b32 vcc_lo, v5
	s_cmp_lt_u32 vcc_lo, 0x2000
	s_cbranch_scc1 .Lhb_lspin_mix
.Lhb_ltop_mix:
	s_mov_b64 exec, 1
	buffer_wbl2 sc1
	v_readlane_b32 vcc_lo, v255, 55
	v_readlane_b32 vcc_hi, v254, 7
	s_nop 1
	s_add_i32 vcc_lo, vcc_lo, 1
	v_mov_b32_e32 v2, vcc_hi
	v_writelane_b32 v255, vcc_lo, 55
	v_mov_b32_e32 v0, vcc_lo
	v_readlane_b32 vcc_hi, v254, 8
	v_mov_b32_e32 v5, 1
	s_nop 1
	v_mov_b32_e32 v3, vcc_hi
	s_waitcnt vmcnt(0)
	global_atomic_add v6, v[2:3], v5, off sc0
	v_readlane_b32 vcc_lo, v254, 9
	v_readlane_b32 vcc_hi, v254, 10
	v_lshlrev_b32_e32 v4, 2, v0
	s_waitcnt vmcnt(0)
	v_mov_b32_e32 v2, vcc_lo
	v_mov_b32_e32 v3, vcc_hi
	v_add_u32_e32 v6, 1, v6
	s_nop 0
	v_cmp_eq_u32_e32 vcc, v6, v4
	s_cbranch_vccz .Lhb_twait_mix
	global_atomic_add v[2:3], v5, off
	s_branch .Lhb_lrel_mix
